# v15 + nt on the 32 final f32 output stores of the fused P12 epilogue
# speedup vs baseline: 1.0557x; 1.0006x over previous
;     __device__ __forceinline__ void fused(f32x4 (&acc)[2][2][4][2], const Unit& u, int wr, int wc, int fr, int fq, PG8_LAS unsigned char* lds, int wid, int lane) const {
;     ...
;         const __amdgpu_buffer_rsrc_t orsrc = __builtin_amdgcn_make_buffer_rsrc((void*)outf, (short)0, 16384 * 1024 * 4, 0x00020000);
;         f32x4 nwv[2][2];
; #pragma unroll
;         for (int bj = 0; bj < 2; ++bj)
; #pragma unroll
;             for (int n = 0; n < 2; ++n) nwv[bj][n] = *(const f32x4*)(nw + col0 + bj * HALF + n * 16);
; #pragma unroll
;         for (int ai = 0; ai < 2; ++ai)
; #pragma unroll
;             for (int m = 0; m < 4; ++m) { const int row = u.pm * BM + ai * HALF + wr * 64 + m * 16 + fr; const size_t off = (size_t)row * ldc + col0;
;                 const float rs = rsqrtf(__hip_atomic_load(rowsq + row, __ATOMIC_RELAXED, __HIP_MEMORY_SCOPE_AGENT) * (1.0f / 1024.0f) + 1e-6f);
; #pragma unroll
;                 for (int bj = 0; bj < 2; ++bj)
; #pragma unroll
;                     for (int n = 0; n < 2; ++n) { const f32x4 y = acc[ai][bj][m][n] * rs * nwv[bj][n]; __builtin_amdgcn_raw_buffer_store_b128(__builtin_bit_cast(u32x4, y), orsrc, (unsigned)((off + bj * HALF + n * 16) * 4), 0, 16); } }
.LBB0_1059:
	s_or_b64 exec, exec, s[0:1]
	v_lshl_add_u64 v[0:1], v[128:129], 2, s[56:57]
	s_barrier
	global_load_dwordx4 v[12:15], v[0:1], off
	global_load_dwordx4 v[8:11], v[0:1], off offset:64
	global_load_dwordx4 v[4:7], v[0:1], off offset:512
	s_nop 0
	global_load_dwordx4 v[0:3], v[0:1], off offset:576
	s_nop 0
	global_load_dword v25, v[134:135], off sc1
	v_mov_b32_e32 v180, 0x358637bd
	s_mov_b32 s6, 0x800000
	v_lshlrev_b32_e32 v181, 2, v128
	s_and_b32 s1, s59, 0xffff
	s_mov_b32 s3, 0x20000
	s_brev_b32 s2, 32
	s_mov_b32 s0, s58
	s_waitcnt vmcnt(0)
	v_fmamk_f32 v25, v25, 0x3a800000, v180
	v_mul_f32_e32 v41, 0x4b800000, v25
	v_cmp_gt_f32_e32 vcc, s6, v25
	s_nop 1
	v_cndmask_b32_e32 v25, v25, v41, vcc
	v_rsq_f32_e32 v25, v25
	v_lshl_add_u32 v41, v130, 12, v181
	v_mul_f32_e32 v57, 0x45800000, v25
	v_cndmask_b32_e32 v128, v25, v57, vcc
	v_pk_mul_f32 v[130:131], v[132:133], v[128:129] op_sel_hi:[1,0]
	v_pk_mul_f32 v[126:127], v[126:127], v[128:129] op_sel_hi:[1,0]
	v_pk_mul_f32 v[124:125], v[124:125], v[128:129] op_sel_hi:[1,0]
	v_pk_mul_f32 v[122:123], v[122:123], v[128:129] op_sel_hi:[1,0]
	v_pk_mul_f32 v[132:133], v[116:117], v[128:129] op_sel_hi:[1,0]
	v_pk_mul_f32 v[134:135], v[118:119], v[128:129] op_sel_hi:[1,0]
	v_pk_mul_f32 v[178:179], v[112:113], v[128:129] op_sel_hi:[1,0]
	v_pk_mul_f32 v[128:129], v[114:115], v[128:129] op_sel_hi:[1,0]
	v_pk_mul_f32 v[114:115], v[14:15], v[126:127]
	v_pk_mul_f32 v[112:113], v[12:13], v[130:131]
	v_pk_mul_f32 v[118:119], v[10:11], v[122:123]
	v_pk_mul_f32 v[116:117], v[8:9], v[124:125]
	v_pk_mul_f32 v[124:125], v[6:7], v[134:135]
	v_pk_mul_f32 v[122:123], v[4:5], v[132:133]
	v_pk_mul_f32 v[128:129], v[2:3], v[128:129]
	v_pk_mul_f32 v[126:127], v[0:1], v[178:179]
	buffer_store_dwordx4 v[112:115], v41, s[0:3], 0 offen sc1 nt
	buffer_store_dwordx4 v[116:119], v41, s[0:3], 0 offen offset:64 sc1 nt
	buffer_store_dwordx4 v[122:125], v41, s[0:3], 0 offen offset:512 sc1 nt
	buffer_store_dwordx4 v[126:129], v41, s[0:3], 0 offen offset:576 sc1 nt
	global_load_dword v25, v[138:139], off sc1
	s_waitcnt vmcnt(0)
	v_fmamk_f32 v25, v25, 0x3a800000, v180
	v_mul_f32_e32 v41, 0x4b800000, v25
	v_cmp_gt_f32_e32 vcc, s6, v25
	s_nop 1
	v_cndmask_b32_e32 v25, v25, v41, vcc
	v_rsq_f32_e32 v25, v25
	v_lshl_add_u32 v41, v120, 12, v181
	v_mul_f32_e32 v57, 0x45800000, v25
	v_cndmask_b32_e32 v112, v25, v57, vcc
	v_pk_mul_f32 v[114:115], v[136:137], v[112:113] op_sel_hi:[1,0]
	v_pk_mul_f32 v[110:111], v[110:111], v[112:113] op_sel_hi:[1,0]
	v_pk_mul_f32 v[108:109], v[108:109], v[112:113] op_sel_hi:[1,0]
	v_pk_mul_f32 v[106:107], v[106:107], v[112:113] op_sel_hi:[1,0]
	v_pk_mul_f32 v[116:117], v[100:101], v[112:113] op_sel_hi:[1,0]
	v_pk_mul_f32 v[118:119], v[102:103], v[112:113] op_sel_hi:[1,0]
	v_pk_mul_f32 v[120:121], v[96:97], v[112:113] op_sel_hi:[1,0]
	v_pk_mul_f32 v[112:113], v[98:99], v[112:113] op_sel_hi:[1,0]
	v_pk_mul_f32 v[98:99], v[14:15], v[110:111]
	v_pk_mul_f32 v[96:97], v[12:13], v[114:115]
	v_pk_mul_f32 v[102:103], v[10:11], v[106:107]
	v_pk_mul_f32 v[100:101], v[8:9], v[108:109]
	v_pk_mul_f32 v[108:109], v[6:7], v[118:119]
	v_pk_mul_f32 v[106:107], v[4:5], v[116:117]
	v_pk_mul_f32 v[112:113], v[2:3], v[112:113]
	v_pk_mul_f32 v[110:111], v[0:1], v[120:121]
	buffer_store_dwordx4 v[96:99], v41, s[0:3], 0 offen sc1 nt
	buffer_store_dwordx4 v[100:103], v41, s[0:3], 0 offen offset:64 sc1 nt
	buffer_store_dwordx4 v[106:109], v41, s[0:3], 0 offen offset:512 sc1 nt
	buffer_store_dwordx4 v[110:113], v41, s[0:3], 0 offen offset:576 sc1 nt
	global_load_dword v25, v[142:143], off sc1
	s_waitcnt vmcnt(0)
	v_fmamk_f32 v25, v25, 0x3a800000, v180
	v_mul_f32_e32 v41, 0x4b800000, v25
	v_cmp_gt_f32_e32 vcc, s6, v25
	s_nop 1
	v_cndmask_b32_e32 v25, v25, v41, vcc
	v_rsq_f32_e32 v25, v25
	v_lshl_add_u32 v41, v104, 12, v181
	v_mul_f32_e32 v57, 0x45800000, v25
	v_cndmask_b32_e32 v96, v25, v57, vcc
	v_pk_mul_f32 v[98:99], v[140:141], v[96:97] op_sel_hi:[1,0]
	v_pk_mul_f32 v[94:95], v[94:95], v[96:97] op_sel_hi:[1,0]
	v_pk_mul_f32 v[92:93], v[92:93], v[96:97] op_sel_hi:[1,0]
	v_pk_mul_f32 v[90:91], v[90:91], v[96:97] op_sel_hi:[1,0]
	v_pk_mul_f32 v[100:101], v[84:85], v[96:97] op_sel_hi:[1,0]
	v_pk_mul_f32 v[102:103], v[86:87], v[96:97] op_sel_hi:[1,0]
	v_pk_mul_f32 v[104:105], v[80:81], v[96:97] op_sel_hi:[1,0]
	v_pk_mul_f32 v[96:97], v[82:83], v[96:97] op_sel_hi:[1,0]
	v_pk_mul_f32 v[82:83], v[14:15], v[94:95]
	v_pk_mul_f32 v[80:81], v[12:13], v[98:99]
	v_pk_mul_f32 v[86:87], v[10:11], v[90:91]
	v_pk_mul_f32 v[84:85], v[8:9], v[92:93]
	v_pk_mul_f32 v[92:93], v[6:7], v[102:103]
	v_pk_mul_f32 v[90:91], v[4:5], v[100:101]
	v_pk_mul_f32 v[96:97], v[2:3], v[96:97]
	v_pk_mul_f32 v[94:95], v[0:1], v[104:105]
	buffer_store_dwordx4 v[80:83], v41, s[0:3], 0 offen sc1 nt
	buffer_store_dwordx4 v[84:87], v41, s[0:3], 0 offen offset:64 sc1 nt
	buffer_store_dwordx4 v[90:93], v41, s[0:3], 0 offen offset:512 sc1 nt
	buffer_store_dwordx4 v[94:97], v41, s[0:3], 0 offen offset:576 sc1 nt
	global_load_dword v25, v[146:147], off sc1
	s_waitcnt vmcnt(0)
;     __device__ __forceinline__ void fused(f32x4 (&acc)[2][2][4][2], const Unit& u, int wr, int wc, int fr, int fq, PG8_LAS unsigned char* lds, int wid, int lane) const {
;     ...
;             for (int m = 0; m < 4; ++m) { const int row = u.pm * BM + ai * HALF + wr * 64 + m * 16 + fr; const size_t off = (size_t)row * ldc + col0;
;                 const float rs = rsqrtf(__hip_atomic_load(rowsq + row, __ATOMIC_RELAXED, __HIP_MEMORY_SCOPE_AGENT) * (1.0f / 1024.0f) + 1e-6f);
; #pragma unroll
;                 for (int bj = 0; bj < 2; ++bj)
; #pragma unroll
;                     for (int n = 0; n < 2; ++n) { const f32x4 y = acc[ai][bj][m][n] * rs * nwv[bj][n]; __builtin_amdgcn_raw_buffer_store_b128(__builtin_bit_cast(u32x4, y), orsrc, (unsigned)((off + bj * HALF + n * 16) * 4), 0, 16); } }
	v_fmamk_f32 v25, v25, 0x3a800000, v180
	v_mul_f32_e32 v41, 0x4b800000, v25
	v_cmp_gt_f32_e32 vcc, s6, v25
	s_nop 1
	v_cndmask_b32_e32 v25, v25, v41, vcc
	v_rsq_f32_e32 v25, v25
	v_lshl_add_u32 v41, v88, 12, v181
	v_mul_f32_e32 v57, 0x45800000, v25
	v_cndmask_b32_e32 v80, v25, v57, vcc
	v_pk_mul_f32 v[82:83], v[144:145], v[80:81] op_sel_hi:[1,0]
	v_pk_mul_f32 v[78:79], v[78:79], v[80:81] op_sel_hi:[1,0]
	v_pk_mul_f32 v[76:77], v[76:77], v[80:81] op_sel_hi:[1,0]
	v_pk_mul_f32 v[74:75], v[74:75], v[80:81] op_sel_hi:[1,0]
	v_pk_mul_f32 v[84:85], v[68:69], v[80:81] op_sel_hi:[1,0]
	v_pk_mul_f32 v[86:87], v[70:71], v[80:81] op_sel_hi:[1,0]
	v_pk_mul_f32 v[88:89], v[64:65], v[80:81] op_sel_hi:[1,0]
	v_pk_mul_f32 v[80:81], v[66:67], v[80:81] op_sel_hi:[1,0]
	v_pk_mul_f32 v[66:67], v[14:15], v[78:79]
	v_pk_mul_f32 v[64:65], v[12:13], v[82:83]
	v_pk_mul_f32 v[70:71], v[10:11], v[74:75]
	v_pk_mul_f32 v[68:69], v[8:9], v[76:77]
	v_pk_mul_f32 v[76:77], v[6:7], v[86:87]
	v_pk_mul_f32 v[74:75], v[4:5], v[84:85]
	v_pk_mul_f32 v[80:81], v[2:3], v[80:81]
	v_pk_mul_f32 v[78:79], v[0:1], v[88:89]
	buffer_store_dwordx4 v[64:67], v41, s[0:3], 0 offen sc1 nt
	buffer_store_dwordx4 v[68:71], v41, s[0:3], 0 offen offset:64 sc1 nt
	buffer_store_dwordx4 v[74:77], v41, s[0:3], 0 offen offset:512 sc1 nt
	buffer_store_dwordx4 v[78:81], v41, s[0:3], 0 offen offset:576 sc1 nt
	global_load_dword v25, v[150:151], off sc1
	s_waitcnt vmcnt(0)
	v_fmamk_f32 v25, v25, 0x3a800000, v180
	v_mul_f32_e32 v41, 0x4b800000, v25
	v_cmp_gt_f32_e32 vcc, s6, v25
	s_nop 1
	v_cndmask_b32_e32 v25, v25, v41, vcc
	v_rsq_f32_e32 v25, v25
	v_lshl_add_u32 v41, v72, 12, v181
	v_mul_f32_e32 v57, 0x45800000, v25
	v_cndmask_b32_e32 v64, v25, v57, vcc
	v_pk_mul_f32 v[66:67], v[148:149], v[64:65] op_sel_hi:[1,0]
	v_pk_mul_f32 v[62:63], v[62:63], v[64:65] op_sel_hi:[1,0]
	v_pk_mul_f32 v[60:61], v[60:61], v[64:65] op_sel_hi:[1,0]
	v_pk_mul_f32 v[58:59], v[58:59], v[64:65] op_sel_hi:[1,0]
	v_pk_mul_f32 v[68:69], v[52:53], v[64:65] op_sel_hi:[1,0]
	v_pk_mul_f32 v[70:71], v[54:55], v[64:65] op_sel_hi:[1,0]
	v_pk_mul_f32 v[72:73], v[48:49], v[64:65] op_sel_hi:[1,0]
	v_pk_mul_f32 v[64:65], v[50:51], v[64:65] op_sel_hi:[1,0]
	v_pk_mul_f32 v[50:51], v[14:15], v[62:63]
	v_pk_mul_f32 v[48:49], v[12:13], v[66:67]
	v_pk_mul_f32 v[54:55], v[10:11], v[58:59]
	v_pk_mul_f32 v[52:53], v[8:9], v[60:61]
	v_pk_mul_f32 v[60:61], v[6:7], v[70:71]
	v_pk_mul_f32 v[58:59], v[4:5], v[68:69]
	v_pk_mul_f32 v[64:65], v[2:3], v[64:65]
	v_pk_mul_f32 v[62:63], v[0:1], v[72:73]
	buffer_store_dwordx4 v[48:51], v41, s[0:3], 0 offen sc1 nt
	buffer_store_dwordx4 v[52:55], v41, s[0:3], 0 offen offset:64 sc1 nt
	buffer_store_dwordx4 v[58:61], v41, s[0:3], 0 offen offset:512 sc1 nt
	buffer_store_dwordx4 v[62:65], v41, s[0:3], 0 offen offset:576 sc1 nt
	global_load_dword v25, v[154:155], off sc1
	s_waitcnt vmcnt(0)
;     __device__ __forceinline__ void fused(f32x4 (&acc)[2][2][4][2], const Unit& u, int wr, int wc, int fr, int fq, PG8_LAS unsigned char* lds, int wid, int lane) const {
;     ...
;             for (int m = 0; m < 4; ++m) { const int row = u.pm * BM + ai * HALF + wr * 64 + m * 16 + fr; const size_t off = (size_t)row * ldc + col0;
;                 const float rs = rsqrtf(__hip_atomic_load(rowsq + row, __ATOMIC_RELAXED, __HIP_MEMORY_SCOPE_AGENT) * (1.0f / 1024.0f) + 1e-6f);
; #pragma unroll
;                 for (int bj = 0; bj < 2; ++bj)
; #pragma unroll
;                     for (int n = 0; n < 2; ++n) { const f32x4 y = acc[ai][bj][m][n] * rs * nwv[bj][n]; __builtin_amdgcn_raw_buffer_store_b128(__builtin_bit_cast(u32x4, y), orsrc, (unsigned)((off + bj * HALF + n * 16) * 4), 0, 16); } }
	v_fmamk_f32 v25, v25, 0x3a800000, v180
	v_mul_f32_e32 v41, 0x4b800000, v25
	v_cmp_gt_f32_e32 vcc, s6, v25
	s_nop 1
	v_cndmask_b32_e32 v25, v25, v41, vcc
	v_rsq_f32_e32 v25, v25
	v_lshl_add_u32 v41, v56, 12, v181
	v_mul_f32_e32 v48, 0x45800000, v25
	v_cndmask_b32_e32 v48, v25, v48, vcc
	v_pk_mul_f32 v[50:51], v[152:153], v[48:49] op_sel_hi:[1,0]
	v_pk_mul_f32 v[46:47], v[46:47], v[48:49] op_sel_hi:[1,0]
	v_pk_mul_f32 v[44:45], v[44:45], v[48:49] op_sel_hi:[1,0]
	v_pk_mul_f32 v[42:43], v[42:43], v[48:49] op_sel_hi:[1,0]
	v_pk_mul_f32 v[52:53], v[36:37], v[48:49] op_sel_hi:[1,0]
	v_pk_mul_f32 v[54:55], v[38:39], v[48:49] op_sel_hi:[1,0]
	v_pk_mul_f32 v[56:57], v[32:33], v[48:49] op_sel_hi:[1,0]
	v_pk_mul_f32 v[48:49], v[34:35], v[48:49] op_sel_hi:[1,0]
	v_pk_mul_f32 v[34:35], v[14:15], v[46:47]
	v_pk_mul_f32 v[32:33], v[12:13], v[50:51]
	v_pk_mul_f32 v[38:39], v[10:11], v[42:43]
	v_pk_mul_f32 v[36:37], v[8:9], v[44:45]
	v_pk_mul_f32 v[44:45], v[6:7], v[54:55]
	v_pk_mul_f32 v[42:43], v[4:5], v[52:53]
	v_pk_mul_f32 v[48:49], v[2:3], v[48:49]
	v_pk_mul_f32 v[46:47], v[0:1], v[56:57]
	buffer_store_dwordx4 v[32:35], v41, s[0:3], 0 offen sc1 nt
	buffer_store_dwordx4 v[36:39], v41, s[0:3], 0 offen offset:64 sc1 nt
	buffer_store_dwordx4 v[42:45], v41, s[0:3], 0 offen offset:512 sc1 nt
	buffer_store_dwordx4 v[46:49], v41, s[0:3], 0 offen offset:576 sc1 nt
	global_load_dword v25, v[164:165], off sc1
	v_lshl_add_u32 v42, v40, 12, v181
	s_waitcnt vmcnt(0)
	v_fmamk_f32 v25, v25, 0x3a800000, v180
	v_mul_f32_e32 v32, 0x4b800000, v25
	v_cmp_gt_f32_e32 vcc, s6, v25
	s_nop 1
	v_cndmask_b32_e32 v25, v25, v32, vcc
	v_rsq_f32_e32 v25, v25
	s_nop 0
	v_mul_f32_e32 v32, 0x45800000, v25
	v_cndmask_b32_e32 v32, v25, v32, vcc
	v_pk_mul_f32 v[34:35], v[156:157], v[32:33] op_sel_hi:[1,0]
	v_pk_mul_f32 v[30:31], v[30:31], v[32:33] op_sel_hi:[1,0]
	v_pk_mul_f32 v[28:29], v[28:29], v[32:33] op_sel_hi:[1,0]
	v_pk_mul_f32 v[26:27], v[26:27], v[32:33] op_sel_hi:[1,0]
	v_pk_mul_f32 v[36:37], v[20:21], v[32:33] op_sel_hi:[1,0]
	v_pk_mul_f32 v[38:39], v[22:23], v[32:33] op_sel_hi:[1,0]
	v_pk_mul_f32 v[40:41], v[16:17], v[32:33] op_sel_hi:[1,0]
	v_pk_mul_f32 v[32:33], v[18:19], v[32:33] op_sel_hi:[1,0]
	v_pk_mul_f32 v[18:19], v[14:15], v[30:31]
	v_pk_mul_f32 v[16:17], v[12:13], v[34:35]
	v_pk_mul_f32 v[22:23], v[10:11], v[26:27]
	v_pk_mul_f32 v[20:21], v[8:9], v[28:29]
	v_pk_mul_f32 v[28:29], v[6:7], v[38:39]
	v_pk_mul_f32 v[26:27], v[4:5], v[36:37]
	v_pk_mul_f32 v[32:33], v[2:3], v[32:33]
	v_pk_mul_f32 v[30:31], v[0:1], v[40:41]
	buffer_store_dwordx4 v[16:19], v42, s[0:3], 0 offen sc1 nt
	buffer_store_dwordx4 v[20:23], v42, s[0:3], 0 offen offset:64 sc1 nt
	buffer_store_dwordx4 v[26:29], v42, s[0:3], 0 offen offset:512 sc1 nt
	buffer_store_dwordx4 v[30:33], v42, s[0:3], 0 offen offset:576 sc1 nt
	global_load_dword v16, v[176:177], off sc1
	s_waitcnt vmcnt(0)
	v_fmac_f32_e32 v180, 0x3a800000, v16
	v_mul_f32_e32 v16, 0x4b800000, v180
	v_cmp_gt_f32_e32 vcc, s6, v180
	v_lshl_add_u32 v32, v24, 12, v181
	s_nop 0
	v_cndmask_b32_e32 v16, v180, v16, vcc
	v_rsq_f32_e32 v16, v16
	s_nop 0
	v_mul_f32_e32 v17, 0x45800000, v16
	v_cndmask_b32_e32 v16, v16, v17, vcc
	v_pk_mul_f32 v[18:19], v[174:175], v[16:17] op_sel_hi:[1,0]
	v_pk_mul_f32 v[20:21], v[172:173], v[16:17] op_sel_hi:[1,0]
	v_pk_mul_f32 v[22:23], v[170:171], v[16:17] op_sel_hi:[1,0]
	v_pk_mul_f32 v[24:25], v[168:169], v[16:17] op_sel_hi:[1,0]
	v_pk_mul_f32 v[26:27], v[166:167], v[16:17] op_sel_hi:[1,0]
	v_pk_mul_f32 v[28:29], v[160:161], v[16:17] op_sel_hi:[1,0]
	v_pk_mul_f32 v[30:31], v[162:163], v[16:17] op_sel_hi:[1,0]
	v_pk_mul_f32 v[16:17], v[158:159], v[16:17] op_sel_hi:[1,0]
	v_pk_mul_f32 v[14:15], v[14:15], v[20:21]
	v_pk_mul_f32 v[12:13], v[12:13], v[18:19]
	v_pk_mul_f32 v[10:11], v[10:11], v[24:25]
	v_pk_mul_f32 v[8:9], v[8:9], v[22:23]
	v_pk_mul_f32 v[6:7], v[6:7], v[28:29]
	v_pk_mul_f32 v[4:5], v[4:5], v[26:27]
	v_pk_mul_f32 v[2:3], v[2:3], v[16:17]
	v_pk_mul_f32 v[0:1], v[0:1], v[30:31]
	buffer_store_dwordx4 v[12:15], v32, s[0:3], 0 offen sc1 nt
	buffer_store_dwordx4 v[8:11], v32, s[0:3], 0 offen offset:64 sc1 nt
	buffer_store_dwordx4 v[4:7], v32, s[0:3], 0 offen offset:512 sc1 nt
	buffer_store_dwordx4 v[0:3], v32, s[0:3], 0 offen offset:576 sc1 nt
